# v72 + T5 bias table (depends only on the head = blockIdx&3) filled in the workgroup's first diff unit only
# speedup vs baseline: 1.0048x; 1.0048x over previous
; #define LAS __attribute__((address_space(3)))
; DI void phase4(const Params& p, LAS unsigned char* lds, int wv) {
;     unsigned char* ws = p.ws;
;     const bf16_t* P = (const bf16_t*)(ws + WS_P); const bf16_t* Q = (const bf16_t*)(ws + WS_Q); const bf16_t* KM = (const bf16_t*)(ws + WS_KM); const bf16_t* V = (const bf16_t*)(ws + WS_V);
;     bf16_t* AO = (bf16_t*)(ws + WS_AO); float* S0 = (float*)(ws + WS_S0); const float lam = ((const float*)(ws + WS_MISC))[0];
;     for (int L = blockIdx.x; L < 2048; L += gridDim.x) {
;         const int i = L >> 8, c = L & 255, x = c & 7, j = c >> 3, g = i * 8 + x, b = g >> 2, h = g & 3, kind = ((j >> 4) + i) & 1, qb = j & 15;
;         const size_t rowbase = (size_t)b * SEQ, qrow = rowbase + qb * 256;
.LBB0_1908:
	s_mov_b32 s32, 0
	v_readlane_b32 s0, v255, 2
	s_add_u32 s60, s34, 0x28000000
	v_readlane_b32 s1, v255, 3
	s_addc_u32 s61, s35, 0
	s_and_b64 vcc, exec, s[0:1]
	s_barrier
	s_cbranch_vccnz .LBB0_1986
	v_mov_b32_e32 v0, 0x32e00000
	global_load_dword v128, v0, s[34:35]
	s_add_u32 s0, s34, 0x34000000
	v_writelane_b32 v255, s0, 2
	s_addc_u32 s0, s35, 0
	s_lshl_b32 s73, s10, 5
	s_lshl_b32 s25, s11, 5
	v_writelane_b32 v255, s0, 0
	s_add_u32 s0, s34, 0x80c0800
	s_addc_u32 s76, s35, 0
	s_add_u32 s77, s34, 0x8080c00
	s_addc_u32 s78, s35, 0
	s_add_u32 s79, s34, 0x80c0880
	s_movk_i32 s72, 0xe0
	s_mov_b64 s[96:97], 0xc00
	s_movk_i32 s63, 0xffc0
	s_mov_b64 s[8:9], 0x40000
	v_mov_b32_e32 v131, 0
	s_movk_i32 s64, 0x70
	s_movk_i32 s65, 0x60
	s_movk_i32 s66, 0x118
	s_brev_b32 s24, 60
	s_mov_b32 s67, 0x800000
	s_movk_i32 s68, 0x7fff
	s_mov_b32 s69, 0x2aaaaaab
	s_movk_i32 s70, 0x300
	s_mov_b64 s[36:37], 0x18000
	s_mov_b64 s[38:39], 0x10000
	v_mov_b32_e32 v160, 0x358637bd
	s_mov_b32 s71, s10
	v_writelane_b32 v255, s0, 6
	s_addc_u32 s80, s35, 0
	s_add_i32 s81, 0, 0x24f00
	s_add_i32 s82, 0, 0x15000
	s_mov_b32 s83, s10
	s_waitcnt vmcnt(0)
	v_mov_b32_e32 v129, v128
	s_branch .LBB0_1912

; #define LAS __attribute__((address_space(3)))
; template <int TAG = 0> DI int fresh_tid(int wv) { int l; asm volatile("v_mbcnt_lo_u32_b32 %0, -1, 0\n\tv_mbcnt_hi_u32_b32 %0, -1, %0 ; site %1" : "=v"(l) : "n"(TAG)); return wv * 64 + l; }
; DI void phase4(const Params& p, LAS unsigned char* lds, int wv) {
;     ...
;     for (int L = blockIdx.x; L < 2048; L += gridDim.x) {
;         const int i = L >> 8, c = L & 255, x = c & 7, j = c >> 3, g = i * 8 + x, b = g >> 2, h = g & 3, kind = ((j >> 4) + i) & 1, qb = j & 15;
;         const size_t rowbase = (size_t)b * SEQ, qrow = rowbase + qb * 256;
;         if (kind == 0) {
;             att::attn_body<192, 0, 768, 768, 512>(Q + qrow * 768 + h * 192, KM + rowbase * 768 + h * 192, V + rowbase * 512 + h * 128, qb * 256, 0.07216878364870322f * LOG2E,
;                                                  p.mla_q_norm_w, nullptr, AO + qrow * 1024 + h * 128, 0.f, nullptr, lds, wv);
;             __syncthreads();
;         } else {
;             LAS float* bt = (LAS float*)(lds + att::BT_OFF);
;             const int tid = fresh_tid<4>(wv);
;             if (tid < 449) { const int rel = tid - 224, n = rel < 0 ? -rel : rel;
;                 int lg = 8 + (n >= 12) + (n >= 16) + (n >= 23) + (n >= 32) + (n >= 46) + (n >= 64) + (n >= 91); const int bucket = (rel > 0 ? 16 : 0) + (n < 8 ? n : lg);
;                 bt[tid] = p.rel_bias[bucket * 4 + h] * LOG2E; }
.LBB0_1912:
	s_ashr_i32 s0, s83, 8
	s_and_b32 s1, s83, 4
	s_lshl_b32 s2, s0, 3
	s_or_b32 s1, s2, s1
	s_ashr_i32 s42, s1, 2
	s_lshr_b32 s1, s83, 7
	s_add_i32 s1, s1, s0
	s_ashr_i32 s43, s42, 31
	s_lshl_b32 s0, s83, 5
	s_and_b32 s85, s71, 3
	s_lshl_b64 s[40:41], s[42:43], 12
	s_and_b32 s89, s0, 0xf00
	s_lshl_b32 s84, s85, 8
	s_and_b32 s86, s83, 3
	s_or_b32 s40, s40, s89
	s_bitcmp1_b32 s1, 0
	s_cselect_b64 s[0:1], -1, 0
	s_mov_b64 s[2:3], -1
	s_and_b64 vcc, exec, s[0:1]
	s_cbranch_vccz .LBB0_1978
	v_mbcnt_lo_u32_b32 v0, -1, 0
	v_mbcnt_hi_u32_b32 v0, -1, v0
	s_movk_i32 s0, 0x1c1
	v_add_u32_e32 v0, s33, v0
	v_cmp_gt_i32_e32 vcc, s0, v0
	s_cmp_lg_u32 s32, 0
	s_cselect_b64 vcc, 0, vcc
	s_and_saveexec_b64 s[2:3], vcc
	s_cbranch_execz .LBB0_1915
	s_movk_i32 s1, 0xe0
	v_add_u32_e32 v1, 0xffffff20, v0
	v_sub_u32_e32 v2, 0xe0, v0
	v_cmp_gt_i32_e32 vcc, s1, v0
	s_movk_i32 s0, 0x5a
	s_movk_i32 s72, 0xe0
	v_cndmask_b32_e32 v1, v1, v2, vcc
	v_cmp_lt_i32_e32 vcc, 11, v1
	s_nop 1
	v_cndmask_b32_e64 v2, 8, 9, vcc
	v_cmp_lt_i32_e32 vcc, 15, v1
	s_nop 1
	v_cndmask_b32_e64 v3, 0, 1, vcc
	v_cmp_lt_i32_e32 vcc, 22, v1
	s_nop 1
	v_addc_co_u32_e32 v2, vcc, v2, v3, vcc
	v_cmp_lt_i32_e32 vcc, 31, v1
	s_nop 1
	v_cndmask_b32_e64 v3, 0, 1, vcc
	v_cmp_lt_i32_e32 vcc, 45, v1
	s_nop 1
	v_addc_co_u32_e32 v2, vcc, v2, v3, vcc
	v_cmp_lt_i32_e32 vcc, 63, v1
	s_nop 1
	v_cndmask_b32_e64 v3, 0, 1, vcc
	v_cmp_lt_i32_e32 vcc, s0, v1
	s_nop 1
	v_addc_co_u32_e32 v2, vcc, v2, v3, vcc
	v_cmp_lt_i32_e32 vcc, s1, v0
	v_lshl_add_u32 v0, v0, 2, 0
	v_add_u32_e32 v0, 0x24800, v0
	v_cndmask_b32_e64 v3, 0, 16, vcc
	v_cmp_gt_i32_e32 vcc, 8, v1
	s_nop 1
	v_cndmask_b32_e32 v1, v2, v1, vcc
	v_add_u32_e32 v1, v1, v3
	v_lshl_or_b32 v2, v1, 2, s86
	v_ashrrev_i32_e32 v3, 31, v2
	v_lshl_add_u64 v[2:3], v[2:3], 2, s[28:29]
	global_load_dword v1, v[2:3], off
	s_waitcnt vmcnt(0)
	v_mul_f32_e32 v1, 0x3fb8aa3b, v1
	ds_write_b32 v0, v1
; template <int DQK, int MODE, int LDQ, int LDK, int LDV> ...
;     ...
;     for (int i = 0; i < NKP; ++i) { const int L = (wid + 8 * i) * 64 + lane, row = L / CPR, slot = L % CPR, cc = (slot & ~7) | ((slot & 7) ^ ((row >> 1) & 7)); kgo[i] = row * LDK + cc * 8; }
; #pragma unroll
;     for (int i = 0; i < 2; ++i) { const int L = (2 * wid + i) * 64 + lane, st = L >> 5, w5 = L & 31, kk = (st >> 2) * 8 + (w5 >> 2), c = (st & 3) * 32 + (w5 & 3) * 8;
;         const int k = (kk & ~0xC) | ((kk & 4) << 1) | ((kk & 8) >> 1); vgo[i] = k * LDV + c; }
;     ...
;     ATT_DMA_K(0); ATT_DMA_K(1); ATT_DMA_V(0, 0); ATT_DMA_K(2); ATT_DMA_V(1, 1);
;     bf16x8 qr[ND0];
;     { const bf16_t* Qw = Qb + (size_t)(wid * 32 + r32) * LDQ + hi * 8;
; #pragma unroll
;       for (int d0 = 0; d0 < ND0; ++d0) qr[d0] = *(const bf16x8*)(Qw + d0 * 16);
;       if constexpr (MODE == 0) {
;           float ss = 0.f;
; #pragma unroll
;           for (int d0 = 0; d0 < ND0; ++d0)
; #pragma unroll
;               for (int j = 0; j < 8; ++j) { const float f = bf2f((unsigned short)qr[d0][j]); ss += f * f; }
;           ss = swap_sum(ss);
;           const float rstd = rsqrtf(ss * (1.f / DQK) + EPS) * C;
; #pragma unroll
;           for (int d0 = 0; d0 < ND0; ++d0) { const float* g = gq + d0 * 16 + hi * 8;
;               { float f[8]; _Pragma("unroll") for (int j = 0; j < 8; ++j) f[j] = bf2f((unsigned short)qr[d0][j]) * rstd * g[j];
;                 u32x4 w = {cvtpk(f[0], f[1]), cvtpk(f[2], f[3]), cvtpk(f[4], f[5]), cvtpk(f[6], f[7])}; qr[d0] = __builtin_bit_cast(bf16x8, w); asm volatile("" ::: "memory"); } }
;       } }
;     const int qlo = q0 + wid * 32, qpos = qlo + r32;
;     const int tL = MODE == 0 ? 0 : (qlo >= 191 ? (qlo - 127) >> 6 : 0), tR = MODE == 0 ? NT : min(NT, (qlo + 222) >> 6);
;     float fL = 1.f, fR = 1.f; if constexpr (MODE != 0) { fL = __builtin_amdgcn_exp2f(bt[0]); fR = __builtin_amdgcn_exp2f(-bt[448]); }
;     ...
;     const int vbase = (int)(unsigned)(size_t)lds + V_OFF + v_rd_base(lane);
;     ...
;     constexpr int NDA = ND0 > 6 ? 6 : ND0;
;     ...
;     f32x16 pA, pB; bf16x8 pa0, pa1;
;     int v0 = 0, v1 = 1, v2 = 2;
;     ATT_TOP(NKP + 2);
; DI void phase4(const Params& p, LAS unsigned char* lds, int wv) {
;     ...
;             __syncthreads();
;             att::attn_body<64, 1, 2048, 2048, 2048>(P + qrow * 2048 + 512 + h * 128, P + rowbase * 2048 + 1024 + h * 128, P + rowbase * 2048 + 1536 + h * 128, qb * 256, 0.f,
.LBB0_1915:
	s_or_b64 exec, exec, s[2:3]
	s_mov_b32 s32, 1
	s_lshl_b64 s[0:1], s[40:41], 12
	s_add_u32 s0, s14, s0
	s_addc_u32 s1, s15, s1
	s_lshl_b32 s4, s86, 8
	s_add_u32 s44, s0, s4
	s_addc_u32 s45, s1, 0
	s_lshl_b64 s[2:3], s[42:43], 24
	s_add_u32 s0, s14, s2
	s_addc_u32 s1, s15, s3
	s_add_u32 s46, s0, s4
	s_addc_u32 s47, s1, 0
	s_add_u32 s48, s46, 0x800
	s_waitcnt lgkmcnt(0)
	s_barrier
	s_addc_u32 s49, s47, 0
	v_mbcnt_lo_u32_b32 v7, -1, 0
	v_mbcnt_hi_u32_b32 v7, -1, v7
	s_add_u32 s56, s46, 0xc00
	v_add_u32_e32 v0, s33, v7
	s_addc_u32 s57, s47, 0
	v_readfirstlane_b32 s0, v0
	s_ashr_i32 s4, s0, 31
	s_ashr_i32 s1, s0, 6
	v_mov_b32_e32 v1, s0
	v_bfi_b32 v1, s63, v1, v7
	s_lshr_b32 s4, s4, 29
	v_add_u32_e32 v3, s4, v1
	s_lshl_b32 s4, s1, 7
	v_ashrrev_i32_e32 v9, 3, v3
	v_and_b32_e32 v3, 0x1ffffff8, v3
	s_ashr_i32 s4, s4, 4
	v_bfe_u32 v4, v0, 2, 2
	v_lshrrev_b32_e32 v0, 2, v0
	v_sub_u32_e32 v1, v1, v3
	v_lshrrev_b32_e32 v3, 1, v9
	v_lshlrev_b32_e32 v18, 3, v7
	s_and_b32 s6, s4, -16
	v_and_b32_e32 v6, 4, v0
	s_lshr_b32 s4, s4, 0
	v_bitop3_b32 v1, v3, v1, 7 bitop3:0x6c
	v_and_b32_e32 v3, 32, v7
	v_and_b32_e32 v5, 24, v18
	s_and_b32 s7, s4, 8
	v_or3_b32 v0, v6, v4, s6
	v_or_b32_e32 v10, v3, v5
	v_or_b32_e32 v0, s7, v0
	v_lshl_or_b32 v96, v0, 11, v10
	v_lshlrev_b32_e32 v0, 11, v9
	v_lshl_add_u32 v0, v1, 3, v0
	v_ashrrev_i32_e32 v1, 31, v0
	v_lshlrev_b64 v[10:11], 1, v[0:1]
	v_lshl_add_u64 v[12:13], s[46:47], 0, v[10:11]
	s_mov_b64 s[4:5], 0x800
	v_lshl_add_u64 v[12:13], v[12:13], 0, s[4:5]
	s_lshl_b32 s4, s1, 10
	s_add_i32 s59, s4, 0
	s_mov_b32 m0, s59
	v_lshl_add_u64 v[10:11], s[48:49], 0, v[10:11]
	global_load_lds_dwordx4 v[12:13], off
	v_lshl_add_u64 v[12:13], v[10:11], 0, s[8:9]
	s_add_i32 m0, s59, 0x2000
	s_lshl_b32 s4, s1, 11
	v_ashrrev_i32_e32 v97, 31, v96
	global_load_lds_dwordx4 v[12:13], off
	s_add_i32 s22, s4, 0
	v_lshlrev_b64 v[12:13], 1, v[96:97]
	s_add_i32 s95, s22, 0x18000
	v_lshl_add_u64 v[14:15], s[46:47], 0, v[12:13]
	v_lshl_add_u64 v[16:17], v[14:15], 0, s[96:97]
	s_mov_b32 m0, s95
	s_mov_b64 s[4:5], 0xc80
	global_load_lds_dwordx4 v[16:17], off
	v_lshl_add_u64 v[14:15], v[14:15], 0, s[4:5]
	s_add_i32 m0, s22, 0x18400
	s_mov_b64 s[4:5], 0x80000
	global_load_lds_dwordx4 v[14:15], off
	s_add_i32 m0, s59, 0x4000
	s_add_u32 s52, s46, 0x40c00
	v_or_b32_e32 v98, 64, v96
	v_lshl_add_u64 v[10:11], v[10:11], 0, s[4:5]
	s_addc_u32 s53, s47, 0
	v_ashrrev_i32_e32 v99, 31, v98
	global_load_lds_dwordx4 v[10:11], off
	s_add_i32 m0, s22, 0x1c000
	v_lshl_add_u64 v[10:11], s[52:53], 0, v[12:13]
	v_and_b32_e32 v2, 31, v7
	global_load_lds_dwordx4 v[10:11], off
	v_lshl_add_u64 v[10:11], v[98:99], 1, s[52:53]
	s_add_i32 m0, s22, 0x1c400
	s_lshl_b32 s94, s1, 5
	global_load_lds_dwordx4 v[10:11], off
	v_or_b32_e32 v10, s94, v2
	v_ashrrev_i32_e32 v11, 31, v10
	v_bfe_u32 v8, v7, 5, 1
	v_lshlrev_b64 v[10:11], 12, v[10:11]
	v_lshl_add_u64 v[10:11], s[44:45], 0, v[10:11]
	v_lshlrev_b32_e32 v130, 4, v8
	v_lshl_add_u64 v[10:11], v[10:11], 0, v[130:131]
	global_load_dwordx4 v[92:95], v[10:11], off offset:1024
	global_load_dwordx4 v[88:91], v[10:11], off offset:1056
	global_load_dwordx4 v[84:87], v[10:11], off offset:1088
	global_load_dwordx4 v[80:83], v[10:11], off offset:1120
	s_add_i32 s4, s94, s89
	s_add_i32 s5, s4, 0xffffff81
	s_ashr_i32 s5, s5, 6
	s_cmpk_gt_i32 s4, 0xbe
	s_cselect_b32 s55, s5, 0
	s_add_i32 s88, 0, 0x24800
	v_and_b32_e32 v11, 0x70, v18
	v_mov_b32_e32 v9, s88
	v_mov_b32_e32 v10, s81
	v_lshl_add_u32 v114, v2, 7, 0
	v_bitop3_b32 v115, v130, v18, s64 bitop3:0x78
	v_bitop3_b32 v117, v130, v11, 64 bitop3:0x36
	ds_read_b32 v9, v9
	ds_read_b32 v10, v10
	s_waitcnt vmcnt(3)
	s_barrier
	v_add_u32_e32 v107, v114, v115
	v_bitop3_b32 v116, v130, v11, 32 bitop3:0x36
	v_add_u32_e32 v109, v114, v117
	v_bitop3_b32 v118, v130, v11, s65 bitop3:0x36
	v_add_u32_e32 v108, v114, v116
	ds_read_b128 v[12:15], v107
	ds_read_b128 v[16:19], v108
	v_add_u32_e32 v110, v114, v118
	ds_read_b128 v[20:23], v109
	ds_read_b128 v[24:27], v110
	v_or_b32_e32 v111, s4, v2
	s_addk_i32 s4, 0xde
	s_ashr_i32 s58, s4, 6
	s_waitcnt lgkmcnt(0)
	s_waitcnt vmcnt(0) lgkmcnt(0)
	v_mfma_f32_32x32x16_bf16 v[64:79], v[12:15], v[92:95], 0
	s_cmp_gt_i32 s55, 0
	s_cselect_b64 s[4:5], -1, 0
	s_cmp_lt_i32 s58, 1
	s_cselect_b64 s[22:23], -1, 0
	s_or_b64 s[4:5], s[22:23], s[4:5]
	s_and_b64 vcc, exec, s[4:5]
	v_mfma_f32_32x32x16_bf16 v[64:79], v[16:19], v[88:91], v[64:79]
	v_mfma_f32_32x32x16_bf16 v[64:79], v[20:23], v[84:87], v[64:79]
	v_mfma_f32_32x32x16_bf16 v[64:79], v[24:27], v[80:83], v[64:79]
	s_cbranch_vccnz .LBB0_1917
	v_lshlrev_b32_e32 v8, 2, v8
	v_sub_u32_e32 v8, v8, v111
	v_lshl_add_u32 v8, v8, 2, s88
	ds_read2_b32 v[12:13], v8 offset0:240 offset1:241
	ds_read2_b32 v[14:15], v8 offset0:242 offset1:243
	ds_read2_b32 v[16:17], v8 offset0:248 offset1:249
	ds_read2_b32 v[18:19], v8 offset0:250 offset1:251
	ds_read2_b32 v[20:21], v8 offset0:224 offset1:225
	ds_read2_b32 v[22:23], v8 offset0:226 offset1:227
	ds_read2_b32 v[24:25], v8 offset0:232 offset1:233
	ds_read2_b32 v[26:27], v8 offset0:234 offset1:235
	s_waitcnt lgkmcnt(4)
	v_pk_add_f32 v[78:79], v[78:79], v[18:19]
	v_pk_add_f32 v[76:77], v[76:77], v[16:17]
	v_pk_add_f32 v[74:75], v[74:75], v[14:15]
	v_pk_add_f32 v[72:73], v[72:73], v[12:13]
	s_waitcnt lgkmcnt(0)
	v_pk_add_f32 v[70:71], v[70:71], v[26:27]
	v_pk_add_f32 v[68:69], v[68:69], v[24:25]
	v_pk_add_f32 v[66:67], v[66:67], v[22:23]
	v_pk_add_f32 v[64:65], v[64:65], v[20:21]
